# GDN chains moved into the merged mixer phase (blocks 0..31 first), completion published with release+atomic and awaited (acquire) by the GDN-output items; m1 keeps compress/window/stick-breaking
# speedup vs baseline: 1.2688x; 1.0182x over previous
; DI int tid_() { int t = __builtin_amdgcn_workitem_id_x(); asm volatile("" : "+v"(t)); return t; }
;   unsigned* ctr = (unsigned*)(p.ws + OFF_CNT) + cslot;
;   const int total = 32 + 64 * 24 + 256;
;   bool first = true;
;   for (;;) {
;     const int it = (first ? (int)blockIdx.x : q_pop(ctr, smem) + (int)gridDim.x) + skip; first = false;
;     if (it >= total) break;
;   unsigned* ctr = (unsigned*)(p.ws + OFF_CNT) + cslot;
;   const int total = 2048, wave = tid_() >> 6;
;   bool first = true;
;   for (;;) {
;     const int it = first ? (int)blockIdx.x : q_pop(ctr, smem) + (int)gridDim.x; first = false;
;     if (it >= total) break;
;     if (it < 1024) nsa_group(p, (1023 - it) * 16 + wave * 4, (float*)smem + wave * 1152);
;     else gdn_g3(p, l, it - 1024, smem);
;   }
; }
.Lm2_enter:
	v_readlane_b32 s0, v242, 62
	s_cmp_eq_u32 s0, 1
	s_cbranch_scc1 .Lm2_go
	s_mov_b32 s0, 2
	s_nop 3
	v_writelane_b32 v242, s0, 62
	s_branch .Lm1_entry

; DI int tid_() { int t = __builtin_amdgcn_workitem_id_x(); asm volatile("" : "+v"(t)); return t; }
; DI float bf2f(bf16_t v) { return __uint_as_float(((unsigned)v) << 16); }
; DI float softplus_f(float x) { return x > 20.f ? x : log1pf(expf(x)); }
; DI void gdn_gates(const Params& p, int l, int b, int hh, int s0, float* sG, float* sBeta) {
;   const bf16_t* proj = (const bf16_t*)(p.ws + OFF_BIG); const int tid = tid_();
;   if (tid < 64) { const bf16_t* row = proj + (size_t)(b * S_ + s0 + tid) * LDP;
;     const float a = bf2f(row[C_GA + hh]), bb = bf2f(row[C_GB + hh]);
;     sG[tid] = -expf(p.alog[l * 4 + hh]) * softplus_f(a + p.dtb[l * 4 + hh]); sBeta[tid] = 1.f / (1.f + expf(-bb)); }
; DI void gdn_g3(const Params& p, int l, int ch, char* smem) {
;   const int b = ch >> 9, hh = (ch >> 7) & 3, n = ch & 127, s0 = n * 64, tid = tid_(), c = tid >> 2, part = tid & 3;
;   float* B1 = (float*)smem; float* B2 = B1 + 64 * 68; float* B3 = B2 + 64 * 68; float* sG = B3 + 64 * 68; float* sBeta = sG + 64;
;   const float* Vn = (const float*)(p.ws + OFF_GU_) + (size_t)ch * 4096; const float* Sg = (const float*)(p.ws + OFF_GS) + (size_t)ch * 4096;
;   __syncthreads();
;   gdn_gates(p, l, b, hh, s0, sG, sBeta);
.LBB0_103:
	s_cmpk_gt_i32 s8, 0x7ff
	s_mov_b64 s[0:1], -1
	s_cbranch_scc1 .LBB0_102
	s_cmpk_gt_i32 s8, 0x3ff
	s_cbranch_scc0 .LBB0_148
	v_readlane_b32 s0, v244, 25
	v_readlane_b32 s1, v244, 26
	s_mov_b32 s9, 0x40000
	s_nop 4
.Lg3_spin:
	global_load_dword v0, v143, s[0:1] offset:36 sc1
	s_waitcnt vmcnt(0)
	v_readfirstlane_b32 s2, v0
	s_cmpk_ge_u32 s2, 0x80
	s_cbranch_scc1 .Lg3_go
	s_sleep 1
	s_add_i32 s9, s9, -1
	s_cmp_lg_u32 s9, 0
	s_cbranch_scc1 .Lg3_spin
.Lg3_go:
	buffer_inv sc1
	s_waitcnt vmcnt(0)
	s_add_i32 s11, s8, 0xfffffc00
	s_lshl_b32 s0, s11, 6
	v_mov_b32_e32 v96, v170
	v_mov_b32_e32 v0, v170
	s_lshr_b32 s12, s11, 9
	s_bfe_u32 s13, s8, 0x20007
	s_and_b32 s9, s0, 0x1fc0
	s_barrier
	s_nop 0
	v_cmp_gt_i32_e64 s[0:1], 64, v0
	s_and_saveexec_b64 s[4:5], s[0:1]
	s_cbranch_execz .LBB0_109
	s_lshl_b32 s2, s12, 13
	v_readlane_b32 s6, v245, 54
	s_or_b32 s2, s9, s2
	v_readlane_b32 s7, v245, 55
	v_add_u32_e32 v1, s2, v0
	s_movk_i32 s2, 0x1a00
	v_mov_b64_e32 v[2:3], s[6:7]
	v_mad_i64_i32 v[2:3], s[6:7], v1, s2, v[2:3]
	s_lshl_b32 s2, s13, 1
	v_lshl_add_u64 v[2:3], v[2:3], 0, s[2:3]
	v_add_co_u32_e32 v2, vcc, 0x1000, v2
	s_or_b32 s6, s13, s62
	s_nop 0
	v_addc_co_u32_e32 v3, vcc, 0, v3, vcc
	global_load_ushort v1, v[2:3], off offset:2304
	s_ashr_i32 s7, s6, 31
	v_readlane_b32 s64, v245, 36
	s_lshl_b64 s[6:7], s[6:7], 2
	v_readlane_b32 s70, v245, 42
	v_readlane_b32 s71, v245, 43
	s_add_u32 s20, s70, s6
	v_readlane_b32 s72, v245, 44
	s_addc_u32 s21, s71, s7
	v_readlane_b32 s73, v245, 45
	s_add_u32 s6, s72, s6
	s_addc_u32 s7, s73, s7
	s_mov_b32 s2, 0x41a00000
	v_readlane_b32 s65, v245, 37
	v_readlane_b32 s66, v245, 38
	v_readlane_b32 s67, v245, 39
	v_readlane_b32 s68, v245, 40
	v_readlane_b32 s69, v245, 41
	v_readlane_b32 s74, v245, 46
	v_readlane_b32 s75, v245, 47
	v_readlane_b32 s76, v245, 48
	v_readlane_b32 s77, v245, 49
	v_readlane_b32 s78, v245, 50
	v_readlane_b32 s79, v245, 51
	s_waitcnt vmcnt(0)
	v_lshlrev_b32_e32 v4, 16, v1
	global_load_ushort v1, v[2:3], off offset:2312
	s_nop 0
	global_load_dword v2, v143, s[20:21]
	global_load_dword v3, v143, s[6:7]
	s_waitcnt vmcnt(0)
	v_add_f32_e32 v3, v3, v4
	v_cmp_nlt_f32_e32 vcc, s2, v3
	s_and_saveexec_b64 s[6:7], vcc
	s_cbranch_execz .LBB0_108
	v_mul_f32_e32 v4, 0x3fb8aa3b, v3
	v_rndne_f32_e32 v5, v4
	s_mov_b32 s2, 0x3fb8aa3b
	v_sub_f32_e32 v6, v4, v5
	v_fma_f32 v4, v3, s2, -v4
	v_fmac_f32_e32 v4, 0x32a5705f, v3
	v_add_f32_e32 v4, v6, v4
	v_cvt_i32_f32_e32 v5, v5
	v_exp_f32_e32 v4, v4
	s_mov_b32 s2, 0xc2ce8ed0
	v_cmp_ngt_f32_e32 vcc, s2, v3
	s_mov_b32 s2, 0x42b17218
	v_ldexp_f32 v4, v4, v5
	v_cndmask_b32_e32 v4, 0, v4, vcc
	v_cmp_nlt_f32_e32 vcc, s2, v3
	s_mov_b32 s2, 0x3f2aaaab
	s_nop 0
	v_cndmask_b32_e32 v3, v187, v4, vcc
	v_add_f32_e32 v6, 1.0, v3
	v_add_f32_e32 v4, -1.0, v6
	v_sub_f32_e32 v5, v4, v6
	v_add_f32_e32 v5, 1.0, v5
	v_sub_f32_e32 v4, v3, v4
	v_add_f32_e32 v7, v4, v5
	v_frexp_mant_f32_e32 v8, v6
	v_cvt_f64_f32_e32 v[4:5], v6
	v_frexp_exp_i32_f64_e32 v4, v[4:5]
	v_cmp_gt_f32_e32 vcc, s2, v8
	s_mov_b32 s2, 0x3f317218
	s_nop 0
	v_subbrev_co_u32_e32 v12, vcc, 0, v4, vcc
	v_sub_u32_e32 v4, 0, v12
	v_ldexp_f32 v5, v6, v4
	v_add_f32_e32 v6, -1.0, v5
	v_add_f32_e32 v8, 1.0, v5
	v_ldexp_f32 v4, v7, v4
	v_add_f32_e32 v7, 1.0, v6
	v_add_f32_e32 v9, -1.0, v8
	v_sub_f32_e32 v7, v5, v7
	v_sub_f32_e32 v5, v5, v9
	v_add_f32_e32 v7, v4, v7
	v_add_f32_e32 v4, v4, v5
	v_add_f32_e32 v13, v8, v4
	v_rcp_f32_e32 v15, v13
	v_sub_f32_e32 v5, v8, v13
	v_add_f32_e32 v14, v4, v5
	v_add_f32_e32 v5, v6, v7
	v_mul_f32_e32 v17, v5, v15
	v_sub_f32_e32 v4, v6, v5
	v_mul_f32_e32 v6, v13, v17
	v_fma_f32 v8, v17, v13, -v6
	v_fmac_f32_e32 v8, v17, v14
	v_add_f32_e32 v16, v7, v4
	v_add_f32_e32 v4, v6, v8
	v_sub_f32_e32 v7, v5, v4
	v_pk_add_f32 v[10:11], v[4:5], v[6:7] neg_lo:[0,1] neg_hi:[0,1]
	v_mov_b32_e32 v9, v4
	v_pk_add_f32 v[4:5], v[10:11], v[8:9] neg_lo:[0,1] neg_hi:[0,1]
	s_nop 0
	v_add_f32_e32 v5, v16, v5
	v_add_f32_e32 v4, v4, v5
	v_add_f32_e32 v5, v7, v4
	v_mul_f32_e32 v16, v15, v5
	v_mul_f32_e32 v6, v13, v16
	v_fma_f32 v8, v16, v13, -v6
	v_fmac_f32_e32 v8, v16, v14
	v_sub_f32_e32 v7, v7, v5
	v_add_f32_e32 v13, v4, v7
	v_add_f32_e32 v4, v6, v8
	v_sub_f32_e32 v7, v5, v4
	v_pk_add_f32 v[10:11], v[4:5], v[6:7] neg_lo:[0,1] neg_hi:[0,1]
	v_mov_b32_e32 v9, v4
	v_pk_add_f32 v[4:5], v[10:11], v[8:9] neg_lo:[0,1] neg_hi:[0,1]
	s_nop 0
	v_add_f32_e32 v5, v13, v5
	v_add_f32_e32 v4, v4, v5
	v_add_f32_e32 v5, v17, v16
	v_add_f32_e32 v4, v7, v4
	v_sub_f32_e32 v6, v5, v17
	v_mul_f32_e32 v4, v15, v4
	v_sub_f32_e32 v6, v16, v6
	v_add_f32_e32 v6, v6, v4
	v_add_f32_e32 v8, v5, v6
	v_mul_f32_e32 v9, v8, v8
	v_fmamk_f32 v4, v9, 0x3e9b6dac, v172
	v_fmaak_f32 v145, v9, v4, 0x3f2aaada
	v_cvt_f32_i32_e32 v4, v12
	v_sub_f32_e32 v5, v8, v5
	v_sub_f32_e32 v5, v6, v5
	v_ldexp_f32 v10, v5, 1
	v_mul_f32_e32 v5, v8, v9
	v_ldexp_f32 v7, v8, 1
	v_pk_mul_f32 v[8:9], v[4:5], v[144:145]
	s_nop 0
	v_fma_f32 v6, v4, s2, -v8
	v_fmac_f32_e32 v6, 0xb102e308, v4
	v_pk_add_f32 v[4:5], v[8:9], v[6:7]
	s_mov_b32 s2, 0x7f800000
	v_sub_f32_e32 v7, v5, v7
	v_sub_f32_e32 v7, v9, v7
	v_add_f32_e32 v11, v10, v7
	v_mov_b32_e32 v10, v8
	v_pk_add_f32 v[8:9], v[4:5], v[8:9] neg_lo:[0,1] neg_hi:[0,1]
	v_pk_add_f32 v[12:13], v[4:5], v[10:11]
	v_mov_b32_e32 v7, v4
	v_mov_b32_e32 v9, v13
	v_pk_add_f32 v[14:15], v[6:7], v[8:9] neg_lo:[0,1] neg_hi:[0,1]
	v_pk_add_f32 v[6:7], v[6:7], v[8:9]
	v_mov_b32_e32 v10, v11
	v_pk_add_f32 v[8:9], v[6:7], v[4:5] op_sel:[1,0] op_sel_hi:[0,1] neg_lo:[0,1] neg_hi:[0,1]
	v_pk_add_f32 v[16:17], v[12:13], v[8:9] op_sel_hi:[1,0] neg_lo:[0,1] neg_hi:[0,1]
	v_mov_b32_e32 v12, v13
	v_mov_b32_e32 v13, v7
	v_pk_mov_b32 v[8:9], v[4:5], v[8:9] op_sel:[1,0]
	v_mov_b32_e32 v11, v4
	v_pk_add_f32 v[8:9], v[12:13], v[8:9] neg_lo:[0,1] neg_hi:[0,1]
	v_mov_b32_e32 v16, v14
	v_pk_add_f32 v[4:5], v[10:11], v[8:9] neg_lo:[0,1] neg_hi:[0,1]
	v_mov_b32_e32 v15, v7
	v_pk_add_f32 v[8:9], v[16:17], v[4:5]
	v_cmp_neq_f32_e32 vcc, s2, v3
	v_pk_add_f32 v[10:11], v[8:9], v[8:9] op_sel:[0,1] op_sel_hi:[1,0]
	s_mov_b32 s2, 0x33800000
	v_pk_add_f32 v[6:7], v[6:7], v[10:11] op_sel:[1,0] op_sel_hi:[0,1]
	v_mov_b32_e32 v9, v6
	v_pk_add_f32 v[12:13], v[8:9], v[14:15] neg_lo:[0,1] neg_hi:[0,1]
	v_mov_b32_e32 v5, v10
	v_sub_f32_e32 v7, v8, v12
	v_pk_add_f32 v[4:5], v[4:5], v[12:13] neg_lo:[0,1] neg_hi:[0,1]
	v_sub_f32_e32 v7, v14, v7
	v_add_f32_e32 v4, v4, v7
	v_add_f32_e32 v4, v4, v5
	v_add_f32_e32 v4, v6, v4
	v_cndmask_b32_e32 v4, v187, v4, vcc
	v_cmp_lt_f32_e64 vcc, |v3|, s2
	s_nop 1
	v_cndmask_b32_e32 v3, v4, v3, vcc

;     ...
;     const int it = (first ? (int)blockIdx.x : q_pop(ctr, smem) + (int)gridDim.x) + skip; first = false;
;     if (it >= total) break;
;     ...
;     if (it < 32) { if (M1SEL & 1) gdn_chain(p, it, smem); }
;     else if (it < 32 + 256) { if (M1SEL & 16) nsa_compress(p, l, it - 32, smem); }
;     else { const int j = it - 288, kind = j >> 9, jj = j & 511, qb = 63 - (jj >> 3), bh = jj & 7, b = bh >> 2, hh = bh & 3;
;       if (kind == 0) { if (M1SEL & 4) diff_item(p, l, b, hh, qb, smem); } else if (kind == 1) { if (M1SEL & 8) win_item(p, b, hh, qb, smem); } else { if (M1SEL & 2) sb_item(p, b, hh, qb, smem); } }
.LBB0_501:
	v_readlane_b32 s0, v242, 62
	s_cmp_eq_u32 s0, 0
	s_cbranch_scc1 .Lm1_mode0
	s_cmp_eq_u32 s0, 2
	s_cbranch_scc0 .Lm1_mode1
	s_cmp_lt_u32 s11, 32
	s_cbranch_scc1 .Lm1_hdr
	s_mov_b32 s0, 1
	s_nop 3
	v_writelane_b32 v242, s0, 62
.Lm1_mode1:
	s_sub_i32 s11, 0x31f, s11
	s_cmpk_gt_i32 s11, 0x11f
	s_cbranch_scc1 .Lm1_hdr
	s_movk_i32 s11, 0x7ff
	s_branch .Lm1_hdr
.Lm1_mode0:
	s_addk_i32 s11, 0x20
	s_cmpk_lt_u32 s11, 0x120
	s_cbranch_scc1 .Lm1_hdr
	s_addk_i32 s11, 0x200

; DI int tid_() { int t = __builtin_amdgcn_workitem_id_x(); asm volatile("" : "+v"(t)); return t; }
; DI int q_pop(unsigned* ctr, char* smem) {
;   int* sh = (int*)(smem + 65024);
;   __syncthreads();
;   if (tid_() == 0) *sh = (int)atomicAdd(ctr, 1u);
;   __syncthreads();
;   return *sh;
;     ...
;     const int it = (first ? (int)blockIdx.x : q_pop(ctr, smem) + (int)gridDim.x) + skip; first = false;
.LBB0_566:
	v_readlane_b32 s0, v242, 62
	s_cmp_eq_u32 s0, 2
	s_cbranch_scc0 .Lq_normal
	buffer_wbl2 sc1
	s_waitcnt vmcnt(0)
	v_readlane_b32 s0, v244, 25
	v_readlane_b32 s1, v244, 26
	s_mov_b64 s[12:13], exec
	s_mov_b64 exec, 1
	s_nop 4
	global_atomic_add v143, v141, s[0:1] offset:36
	s_mov_b64 exec, s[12:13]
	s_mov_b32 s0, 1
	s_nop 3
	v_writelane_b32 v242, s0, 62
	v_readlane_b32 s11, v242, 15
	s_branch .LBB0_501
